# fourier-branch K order permuted (re|im of a column quad adjacent, prep writes folded weights in the same order): FFT output is one 16-byte store per row instead of two 8-byte stores
# speedup vs baseline: 1.0263x; 1.0263x over previous
; __device__ __forceinline__ unsigned pk2(float lo, float hi) { unsigned r; asm volatile("v_cvt_pk_bf16_f32 %0, %1, %2" : "=v"(r) : "v"(lo), "v"(hi)); return r; }
; __device__ void fft_item(const Params& p, int item, bool isctx, LAS unsigned char* lds) {
;     ...
; #pragma unroll 1
;     for (int i1 = tid; i1 < N; i1 += 512) {
;         const int k = (int)(__brev((unsigned)i1) >> (32 - logN));
;         const int k2 = (N - k) & (N - 1);
;         const int i2 = (int)(__brev((unsigned)k2) >> (32 - logN));
;         float re[4], im[4];
; #pragma unroll
;         for (int f = 0; f < 2; ++f) {
;             const f32x2 X = data[f * N + i1], Y = data[f * N + i2];
;             re[2 * f] = (X.x + Y.x) * hs; im[2 * f] = (X.y - Y.y) * hs; re[2 * f + 1] = (X.y + Y.y) * hs; im[2 * f + 1] = (Y.x - X.x) * hs;
;         }
;         bf16_t* dst = AM + (size_t)(rowbase + k) * 1280 + 768 + g * 128 + cc0;
;         u32x2 o; o.x = pk2(re[0], re[1]); o.y = pk2(re[2], re[3]);
;         *(u32x2*)dst = o;
;         o.x = pk2(im[0], im[1]); o.y = pk2(im[2], im[3]);
;         *(u32x2*)(dst + 64) = o;
;     }
.LBB0_99:
	s_or_b64 exec, exec, s[18:19]
	s_waitcnt lgkmcnt(0)
	s_barrier
	s_and_saveexec_b64 s[18:19], vcc
	s_mov_b32 s11, 0x8d80000
	s_cbranch_execz .LBB0_102
	s_and_b32 s4, s22, 60
	s_mov_b64 s[20:21], 0
	s_lshl_b32 s2, s2, 1
	s_mov_b32 s22, 0
.LBB0_101:
	v_bfrev_b32_e32 v10, v18
	v_sub_u32_sdwa v0, v97, v10 dst_sel:DWORD dst_unused:UNUSED_PAD src0_sel:DWORD src1_sel:BYTE_3
	v_bfrev_b32_sdwa v4, v0 dst_sel:DWORD dst_unused:UNUSED_PAD src0_sel:BYTE_0
	v_lshrrev_b32_e32 v4, 21, v4
	v_add_u32_e32 v4, 0, v4
	ds_read2st64_b64 v[0:3], v14 offset1:4
	ds_read2st64_b64 v[4:7], v4 offset1:4
	s_mov_b32 s23, s3
	v_add_u32_e32 v14, 0x1000, v14
	s_waitcnt lgkmcnt(0)
	v_pk_add_f32 v[8:9], v[0:1], v[4:5]
	v_sub_f32_e32 v1, v1, v5
	v_sub_f32_e32 v0, v4, v0
	v_mul_f32_e32 v11, 0x3b800000, v1
	v_mul_f32_e32 v5, 0x3b800000, v9
	v_mul_f32_e32 v9, 0x3b800000, v0
	v_pk_add_f32 v[0:1], v[2:3], v[6:7]
	v_mul_f32_e32 v8, 0x3b800000, v8
	v_mul_f32_e32 v12, 0x3b800000, v0
	v_sub_f32_e32 v0, v3, v7
	v_mul_f32_e32 v7, 0x3b800000, v0
	v_sub_f32_e32 v0, v6, v2
	v_mul_f32_e32 v6, 0x3b800000, v0
	v_or_b32_sdwa v0, v10, s7 dst_sel:DWORD dst_unused:UNUSED_PAD src0_sel:BYTE_3 src1_sel:DWORD
	v_mul_f32_e32 v13, 0x3b800000, v1
	v_mad_u64_u32 v[0:1], s[4:5], v0, s38, v[132:133]
	v_lshl_add_u64 v[0:1], v[0:1], 0, s[2:3]
	v_lshl_add_u64 v[0:1], v[0:1], 0, s[22:23]
	v_lshl_add_u64 v[2:3], v[0:1], 0, s[54:55]
	v_add_co_u32_e32 v0, vcc, s11, v0
	v_cvt_pk_bf16_f32 v4, v8, v5
	v_cvt_pk_bf16_f32 v5, v12, v13
	s_movk_i32 s4, 0xfeff
	s_nop 0
	v_addc_co_u32_e32 v1, vcc, 0, v1, vcc
	v_cvt_pk_bf16_f32 v7, v7, v6
	v_cvt_pk_bf16_f32 v6, v11, v9
	global_store_dwordx4 v[0:1], v[4:7], off offset:1536
	v_add_u32_e32 v0, 0x200, v18
	v_cmp_lt_i32_e32 vcc, s4, v18
	s_or_b64 s[20:21], vcc, s[20:21]
	v_mov_b32_e32 v18, v0
	s_andn2_b64 exec, exec, s[20:21]
	s_cbranch_execnz .LBB0_101

; __device__ __forceinline__ unsigned pk2(float lo, float hi) { unsigned r; asm volatile("v_cvt_pk_bf16_f32 %0, %1, %2" : "=v"(r) : "v"(lo), "v"(hi)); return r; }
; __device__ void fft_item(const Params& p, int item, bool isctx, LAS unsigned char* lds) {
;     ...
; #pragma unroll 1
;     for (int i1 = tid; i1 < N; i1 += 512) {
;         const int k = (int)(__brev((unsigned)i1) >> (32 - logN));
;         const int k2 = (N - k) & (N - 1);
;         const int i2 = (int)(__brev((unsigned)k2) >> (32 - logN));
;         float re[4], im[4];
; #pragma unroll
;         for (int f = 0; f < 2; ++f) {
;             const f32x2 X = data[f * N + i1], Y = data[f * N + i2];
;             re[2 * f] = (X.x + Y.x) * hs; im[2 * f] = (X.y - Y.y) * hs; re[2 * f + 1] = (X.y + Y.y) * hs; im[2 * f + 1] = (Y.x - X.x) * hs;
;         }
;         bf16_t* dst = AM + (size_t)(rowbase + k) * 1280 + 768 + g * 128 + cc0;
;         u32x2 o; o.x = pk2(re[0], re[1]); o.y = pk2(re[2], re[3]);
;         *(u32x2*)dst = o;
;         o.x = pk2(im[0], im[1]); o.y = pk2(im[2], im[3]);
;         *(u32x2*)(dst + 64) = o;
;     }
.LBB0_172:
	s_or_b64 exec, exec, s[18:19]
	s_waitcnt lgkmcnt(0)
	s_barrier
	s_and_saveexec_b64 s[18:19], vcc
	s_cbranch_execz .LBB0_175
	s_lshl_b32 s4, s6, 2
	s_and_b32 s4, s4, 60
	s_mov_b64 s[20:21], 0
	s_lshl_b32 s2, s2, 1
	s_mov_b32 s22, 0
.LBB0_174:
	v_bfrev_b32_e32 v0, v18
	v_lshrrev_b32_e32 v10, 20, v0
	v_sub_u32_e32 v0, 0, v10
	v_and_b32_e32 v0, 0xfff, v0
	v_bfrev_b32_e32 v4, v0
	v_lshrrev_b32_e32 v4, 17, v4
	v_add_u32_e32 v4, 0, v4
	ds_read2st64_b64 v[0:3], v14 offset1:64
	ds_read2st64_b64 v[4:7], v4 offset1:64
	s_mov_b32 s23, s3
	v_add_u32_e32 v14, 0x1000, v14
	s_waitcnt lgkmcnt(0)
	v_pk_add_f32 v[8:9], v[0:1], v[4:5]
	v_sub_f32_e32 v1, v1, v5
	v_sub_f32_e32 v0, v4, v0
	v_mul_f32_e32 v11, 0x3a800000, v1
	v_mul_f32_e32 v5, 0x3a800000, v9
	v_mul_f32_e32 v9, 0x3a800000, v0
	v_pk_add_f32 v[0:1], v[2:3], v[6:7]
	v_mul_f32_e32 v8, 0x3a800000, v8
	v_mul_f32_e32 v12, 0x3a800000, v0
	v_sub_f32_e32 v0, v3, v7
	v_mul_f32_e32 v7, 0x3a800000, v0
	v_sub_f32_e32 v0, v6, v2
	v_mul_f32_e32 v6, 0x3a800000, v0
	v_or_b32_e32 v0, s7, v10
	v_mul_f32_e32 v13, 0x3a800000, v1
	v_mad_i64_i32 v[0:1], s[4:5], v0, s38, v[132:133]
	v_lshl_add_u64 v[0:1], v[0:1], 0, s[2:3]
	v_lshl_add_u64 v[0:1], v[0:1], 0, s[22:23]
	v_lshl_add_u64 v[2:3], v[0:1], 0, s[54:55]
	v_add_co_u32_e32 v0, vcc, s15, v0
	v_cvt_pk_bf16_f32 v4, v8, v5
	v_cvt_pk_bf16_f32 v5, v12, v13
	s_movk_i32 s4, 0xdff
	s_nop 0
	v_addc_co_u32_e32 v1, vcc, 0, v1, vcc
	v_cvt_pk_bf16_f32 v7, v7, v6
	v_cvt_pk_bf16_f32 v6, v11, v9
	global_store_dwordx4 v[0:1], v[4:7], off offset:1536
	v_add_u32_e32 v0, 0x200, v18
	v_cmp_lt_i32_e32 vcc, s4, v18
	s_or_b64 s[20:21], vcc, s[20:21]
	v_mov_b32_e32 v18, v0
	s_andn2_b64 exec, exec, s[20:21]
	s_cbranch_execnz .LBB0_174

; #define GAS __attribute__((address_space(1)))
; __device__ void phase_prep(const Params& p, LAS unsigned char* lds) {
;     ...
; #pragma unroll 1
;             for (int m0 = 0; m0 < 64; m0 += 16) {
;                 float wv[16];
; #pragma unroll
;                 for (int dd = 0; dd < 16; ++dd) wv[dd] = ((GAS const float*)(unsigned long long)wb)[(size_t)(m0 + dd) * 1024];
;                 asm volatile("" ::: "memory");
; #pragma unroll
;                 for (int dd = 0; dd < 16; ++dd) { const int m = m0 + dd; const float w = wv[dd];
; #pragma unroll
;                     for (int q = 0; q < 8; ++q) a[q] += scr[(m * (8 * co + q)) & 63] * w; }
;             }
.LBB0_693:
	s_lshl_b32 s2, s1, 10
	s_or_b32 s25, s1, 1
	v_lshl_add_u64 v[58:59], s[2:3], 2, v[2:3]
	s_lshl_b32 s2, s25, 10
	s_or_b32 s24, s1, 2
	global_load_dword v80, v[58:59], off
	v_lshl_add_u64 v[58:59], s[2:3], 2, v[2:3]
	s_lshl_b32 s2, s24, 10
	global_load_dword v82, v[58:59], off
	v_lshl_add_u64 v[58:59], s[2:3], 2, v[2:3]
	global_load_dword v86, v[58:59], off
	s_or_b32 s23, s1, 3
	s_lshl_b32 s2, s23, 10
	s_or_b32 s22, s1, 4
	v_lshl_add_u64 v[58:59], s[2:3], 2, v[2:3]
	s_lshl_b32 s2, s22, 10
	s_or_b32 s21, s1, 5
	global_load_dword v88, v[58:59], off
	v_lshl_add_u64 v[58:59], s[2:3], 2, v[2:3]
	s_lshl_b32 s2, s21, 10
	s_or_b32 s20, s1, 6
	global_load_dword v92, v[58:59], off
	v_lshl_add_u64 v[58:59], s[2:3], 2, v[2:3]
	s_lshl_b32 s2, s20, 10
	s_or_b32 s19, s1, 7
	global_load_dword v56, v[58:59], off
	v_lshl_add_u64 v[58:59], s[2:3], 2, v[2:3]
	s_lshl_b32 s2, s19, 10
	s_or_b32 s18, s1, 8
	v_lshl_add_u64 v[60:61], s[2:3], 2, v[2:3]
	s_lshl_b32 s2, s18, 10
	s_or_b32 s15, s1, 9
	v_lshl_add_u64 v[62:63], s[2:3], 2, v[2:3]
	s_lshl_b32 s2, s15, 10
	s_or_b32 s13, s1, 10
	v_lshl_add_u64 v[66:67], s[2:3], 2, v[2:3]
	s_lshl_b32 s2, s13, 10
	s_or_b32 s12, s1, 11
	global_load_dword v58, v[58:59], off
	s_or_b32 s11, s1, 12
	global_load_dword v60, v[60:61], off
	s_or_b32 s10, s1, 13
	global_load_dword v62, v[62:63], off
	s_or_b32 s7, s1, 14
	global_load_dword v64, v[66:67], off
	v_lshl_add_u64 v[66:67], s[2:3], 2, v[2:3]
	s_lshl_b32 s2, s12, 10
	v_lshl_add_u64 v[78:79], s[2:3], 2, v[2:3]
	s_lshl_b32 s2, s11, 10
	global_load_dword v66, v[66:67], off
	s_or_b32 s6, s1, 15
	global_load_dword v68, v[78:79], off
	v_lshl_add_u64 v[78:79], s[2:3], 2, v[2:3]
	s_lshl_b32 s2, s10, 10
	global_load_dword v70, v[78:79], off
	v_lshl_add_u64 v[78:79], s[2:3], 2, v[2:3]
	s_lshl_b32 s2, s7, 10
	v_mul_lo_u32 v59, s1, v77
	global_load_dword v72, v[78:79], off
	v_lshl_add_u64 v[78:79], s[2:3], 2, v[2:3]
	s_lshl_b32 s2, s6, 10
	v_and_b32_e32 v61, 48, v59
	v_add_u32_e32 v59, s1, v59
	global_load_dword v74, v[78:79], off
	v_lshl_add_u64 v[78:79], s[2:3], 2, v[2:3]
	v_and_b32_e32 v63, 32, v59
	global_load_dword v76, v[78:79], off
	v_lshl_add_u32 v61, v61, 2, 0
	v_lshl_add_u32 v63, v63, 2, 0
	v_add_u32_e32 v59, s1, v59
	ds_read_b32 v61, v61
	ds_read_b32 v94, v63
	v_and_b32_e32 v63, 48, v59
	v_lshl_add_u32 v63, v63, 2, 0
	v_lshl_add_u32 v59, s1, 1, v59
	ds_read_b32 v95, v63
	v_and_b32_e32 v63, 48, v59
	v_lshl_add_u32 v63, v63, 2, 0
	v_add_u32_e32 v59, s1, v59
	ds_read_b32 v99, v63
	v_and_b32_e32 v63, 32, v59
	v_add_u32_e32 v59, s1, v59
	v_and_b32_e32 v59, 48, v59
	v_lshl_add_u32 v59, v59, 2, 0
	v_lshl_add_u32 v63, v63, 2, 0
	ds_read_b32 v101, v59
	v_mul_lo_u32 v59, s25, v32
	ds_read_b32 v100, v63
	v_and_b32_e32 v63, 56, v59
	v_lshl_add_u32 v63, v63, 2, 0
	ds_read_b32 v102, v63
	v_add_u32_e32 v63, s25, v59
	v_and_b32_e32 v67, 57, v63
	v_lshl_add_u32 v67, v67, 2, 0
	v_add_u32_e32 v63, s25, v63
	ds_read_b32 v103, v67
	v_and_b32_e32 v67, 58, v63
	v_lshl_add_u32 v67, v67, 2, 0
	v_add_u32_e32 v63, s25, v63
	ds_read_b32 v104, v67
	v_and_b32_e32 v67, 59, v63
	v_lshl_add_u32 v67, v67, 2, 0
	v_lshl_add_u32 v63, s25, 1, v63
	ds_read2_b32 v[78:79], v97 offset1:32
	ds_read_b32 v105, v67
	ds_read2_b32 v[84:85], v108 offset1:4
	v_and_b32_e32 v67, 61, v63
	v_lshl_add_u32 v67, v67, 2, 0
	v_add_u32_e32 v63, s25, v63
	ds_read_b32 v107, v67
	v_and_b32_e32 v67, 62, v63
	v_add_u32_e32 v63, s25, v63
	v_and_b32_e32 v63, 63, v63
	v_lshl_add_u32 v67, v67, 2, 0
	v_lshl_add_u32 v63, v63, 2, 0
	v_add_u32_e32 v59, v59, v32
	ds_read_b32 v118, v67
	ds_read_b32 v119, v63
	v_and_b32_e32 v63, 48, v59
	v_lshl_add_u32 v63, v63, 2, 0
	ds_read_b32 v120, v63
	v_add_u32_e32 v63, s24, v59
	v_and_b32_e32 v67, 50, v63
	v_lshl_add_u32 v67, v67, 2, 0
	v_add_u32_e32 v63, s24, v63
	ds_read_b32 v121, v67
	v_and_b32_e32 v67, 52, v63
	v_lshl_add_u32 v67, v67, 2, 0
	v_add_u32_e32 v63, s24, v63
	ds_read_b32 v122, v67
	v_and_b32_e32 v67, 54, v63
	v_lshl_add_u32 v67, v67, 2, 0
	v_lshl_add_u32 v63, s24, 1, v63
	ds_read_b32 v123, v67
	ds_read2_b32 v[90:91], v109 offset1:8
	v_and_b32_e32 v67, 58, v63
	v_lshl_add_u32 v67, v67, 2, 0
	v_add_u32_e32 v63, s24, v63
	ds_read_b32 v125, v67
	v_and_b32_e32 v67, 60, v63
	v_add_u32_e32 v63, s24, v63
	v_and_b32_e32 v63, 62, v63
	v_lshl_add_u32 v67, v67, 2, 0
	v_lshl_add_u32 v63, v63, 2, 0
	v_add_u32_e32 v59, v59, v32
	ds_read_b32 v126, v67
	ds_read_b32 v127, v63
	v_and_b32_e32 v63, 56, v59
	v_lshl_add_u32 v63, v63, 2, 0
	ds_read_b32 v128, v63
	v_add_u32_e32 v63, s23, v59
	v_and_b32_e32 v67, 59, v63
	v_lshl_add_u32 v67, v67, 2, 0
	v_add_u32_e32 v63, s23, v63
	ds_read_b32 v129, v67
	v_and_b32_e32 v67, 62, v63
	v_lshl_add_u32 v67, v67, 2, 0
	v_add_u32_e32 v63, s23, v63
	ds_read_b32 v130, v67
	v_and_b32_e32 v67, 57, v63
	v_lshl_add_u32 v67, v67, 2, 0
	v_add_u32_e32 v63, s23, v63
	ds_read_b32 v131, v67
	v_and_b32_e32 v67, 60, v63
	v_lshl_add_u32 v67, v67, 2, 0
	v_add_u32_e32 v63, s23, v63
	ds_read_b32 v132, v67
	v_and_b32_e32 v67, 63, v63
	v_lshl_add_u32 v67, v67, 2, 0
	v_add_u32_e32 v63, s23, v63
	ds_read_b32 v133, v67
	v_and_b32_e32 v67, 58, v63
	v_add_u32_e32 v63, s23, v63
	v_and_b32_e32 v63, 61, v63
	v_lshl_add_u32 v67, v67, 2, 0
	v_lshl_add_u32 v63, v63, 2, 0
	v_add_u32_e32 v59, v59, v32
	ds_read_b32 v134, v67
	ds_read_b32 v135, v63
	v_and_b32_e32 v63, 32, v59
	v_lshl_add_u32 v63, v63, 2, 0
	ds_read_b32 v136, v63
	v_add_u32_e32 v63, s22, v59
	v_and_b32_e32 v67, 52, v63
	v_lshl_add_u32 v67, v67, 2, 0
	v_add_u32_e32 v63, s22, v63
	ds_read_b32 v137, v67
	v_and_b32_e32 v67, 40, v63
	s_waitcnt vmcnt(15) lgkmcnt(14)
	v_pk_fma_f32 v[50:51], v[80:81], v[94:95], v[50:51] op_sel_hi:[0,1,1]
	v_lshl_add_u32 v67, v67, 2, 0
	v_add_u32_e32 v63, s22, v63
	s_waitcnt vmcnt(14)
; #define GAS __attribute__((address_space(1)))
; __device__ void phase_prep(const Params& p, LAS unsigned char* lds) {
;     ...
;             for (int m0 = 0; m0 < 64; m0 += 16) {
;                 float wv[16];
; #pragma unroll
;                 for (int dd = 0; dd < 16; ++dd) wv[dd] = ((GAS const float*)(unsigned long long)wb)[(size_t)(m0 + dd) * 1024];
;                 asm volatile("" ::: "memory");
; #pragma unroll
;                 for (int dd = 0; dd < 16; ++dd) { const int m = m0 + dd; const float w = wv[dd];
; #pragma unroll
;                     for (int q = 0; q < 8; ++q) a[q] += scr[(m * (8 * co + q)) & 63] * w; }
;             }
	v_pk_fma_f32 v[50:51], v[82:83], v[104:105], v[50:51] op_sel_hi:[0,1,1]
	v_mov_b32_e32 v98, v78
	v_mul_f32_e32 v61, v80, v61
	ds_read_b32 v138, v67
	v_and_b32_e32 v67, 60, v63
	s_waitcnt vmcnt(13)
	v_pk_fma_f32 v[50:51], v[86:87], v[122:123], v[50:51] op_sel_hi:[0,1,1]
	v_lshl_add_u32 v63, s22, 1, v63
	v_pk_mul_f32 v[122:123], v[80:81], v[98:99] op_sel_hi:[0,1]
	v_lshl_add_u32 v67, v67, 2, 0
	v_mov_b32_e32 v123, v61
	v_add_u32_e32 v61, s22, v63
	ds_read_b32 v139, v67
	v_and_b32_e32 v67, 52, v63
	v_and_b32_e32 v63, 56, v61
	v_add_u32_e32 v61, s22, v61
	v_and_b32_e32 v61, 60, v61
	ds_read2_b32 v[94:95], v110 offset1:16
	v_lshl_add_u32 v67, v67, 2, 0
	v_lshl_add_u32 v63, v63, 2, 0
	v_lshl_add_u32 v61, v61, 2, 0
	ds_read_b32 v105, v67
	v_pk_fma_f32 v[54:55], v[80:81], v[98:99], v[54:55] op_sel_hi:[0,1,1]
	ds_read_b32 v98, v63
	ds_read_b32 v99, v61
	v_mov_b32_e32 v106, v85
	v_pk_add_f32 v[4:5], v[4:5], v[122:123]
	v_pk_fma_f32 v[52:53], v[80:81], v[100:101], v[52:53] op_sel_hi:[0,1,1]
	v_pk_fma_f32 v[54:55], v[82:83], v[106:107], v[54:55] op_sel_hi:[0,1,1]
	s_waitcnt lgkmcnt(14)
	v_mov_b32_e32 v124, v91
	v_pk_fma_f32 v[4:5], v[82:83], v[102:103], v[4:5] op_sel_hi:[0,1,1]
	v_pk_fma_f32 v[52:53], v[82:83], v[118:119], v[52:53] op_sel_hi:[0,1,1]
	v_add_u32_e32 v59, v59, v32
	v_pk_fma_f32 v[54:55], v[86:87], v[124:125], v[54:55] op_sel_hi:[0,1,1]
	v_pk_fma_f32 v[4:5], v[86:87], v[120:121], v[4:5] op_sel_hi:[0,1,1]
	v_pk_fma_f32 v[52:53], v[86:87], v[126:127], v[52:53] op_sel_hi:[0,1,1]
	v_and_b32_e32 v61, 56, v59
	s_waitcnt vmcnt(12) lgkmcnt(12)
	v_pk_fma_f32 v[50:51], v[88:89], v[130:131], v[50:51] op_sel_hi:[0,1,1]
	s_waitcnt lgkmcnt(10)
	v_pk_fma_f32 v[54:55], v[88:89], v[132:133], v[54:55] op_sel_hi:[0,1,1]
	v_pk_fma_f32 v[4:5], v[88:89], v[128:129], v[4:5] op_sel_hi:[0,1,1]
	s_waitcnt lgkmcnt(3)
	v_mov_b32_e32 v104, v95
	v_pk_fma_f32 v[52:53], v[88:89], v[134:135], v[52:53] op_sel_hi:[0,1,1]
	v_lshl_add_u32 v61, v61, 2, 0
	s_waitcnt vmcnt(11)
	v_pk_fma_f32 v[50:51], v[92:93], v[138:139], v[50:51] op_sel_hi:[0,1,1]
	v_pk_fma_f32 v[4:5], v[92:93], v[136:137], v[4:5] op_sel_hi:[0,1,1]
	s_waitcnt lgkmcnt(2)
	v_pk_fma_f32 v[54:55], v[92:93], v[104:105], v[54:55] op_sel_hi:[0,1,1]
	s_waitcnt lgkmcnt(0)
	v_pk_fma_f32 v[52:53], v[92:93], v[98:99], v[52:53] op_sel_hi:[0,1,1]
	ds_read_b32 v92, v61
	v_add_u32_e32 v61, s21, v59
	v_and_b32_e32 v63, 61, v61
	v_lshl_add_u32 v63, v63, 2, 0
	v_add_u32_e32 v61, s21, v61
	ds_read_b32 v93, v63
	v_and_b32_e32 v63, 58, v61
	v_lshl_add_u32 v63, v63, 2, 0
	v_add_u32_e32 v61, s21, v61
	ds_read_b32 v86, v63
	v_and_b32_e32 v63, 63, v61
	v_lshl_add_u32 v63, v63, 2, 0
	v_add_u32_e32 v61, s21, v61
	ds_read_b32 v87, v63
	v_and_b32_e32 v63, 60, v61
	v_lshl_add_u32 v63, v63, 2, 0
	v_add_u32_e32 v61, s21, v61
	ds_read_b32 v82, v63
	v_and_b32_e32 v63, 57, v61
	v_lshl_add_u32 v63, v63, 2, 0
	v_add_u32_e32 v61, s21, v61
	ds_read_b32 v83, v63
	v_and_b32_e32 v63, 62, v61
	v_add_u32_e32 v61, s21, v61
	v_and_b32_e32 v61, 59, v61
	v_lshl_add_u32 v63, v63, 2, 0
	v_lshl_add_u32 v61, v61, 2, 0
	v_add_u32_e32 v59, v59, v32
	ds_read_b32 v80, v63
	ds_read_b32 v81, v61
	v_and_b32_e32 v61, 48, v59
	v_lshl_add_u32 v61, v61, 2, 0
	ds_read_b32 v104, v61
	v_add_u32_e32 v61, s20, v59
	v_and_b32_e32 v63, 54, v61
	v_lshl_add_u32 v63, v63, 2, 0
	v_add_u32_e32 v61, s20, v61
	ds_read_b32 v105, v63
	v_and_b32_e32 v63, 60, v61
	v_lshl_add_u32 v63, v63, 2, 0
	v_add_u32_e32 v61, s20, v61
	ds_read_b32 v100, v63
	v_and_b32_e32 v63, 50, v61
	v_lshl_add_u32 v63, v63, 2, 0
	v_add_u32_e32 v61, s20, v61
	ds_read_b32 v101, v63
	v_and_b32_e32 v63, 56, v61
	v_lshl_add_u32 v63, v63, 2, 0
	v_add_u32_e32 v61, s20, v61
	ds_read_b32 v98, v63
	v_and_b32_e32 v63, 62, v61
	v_lshl_add_u32 v63, v63, 2, 0
	v_add_u32_e32 v61, s20, v61
	ds_read_b32 v99, v63
	v_and_b32_e32 v63, 52, v61
	v_add_u32_e32 v61, s20, v61
	v_and_b32_e32 v61, 58, v61
	v_lshl_add_u32 v63, v63, 2, 0
	v_lshl_add_u32 v61, v61, 2, 0
	v_add_u32_e32 v59, v59, v32
	ds_read_b32 v88, v63
	ds_read_b32 v89, v61
	v_and_b32_e32 v61, 56, v59
	v_lshl_add_u32 v61, v61, 2, 0
	v_add_u32_e32 v59, s19, v59
	ds_read_b32 v118, v61
	v_and_b32_e32 v61, 63, v59
	v_lshl_add_u32 v61, v61, 2, 0
	ds_read_b32 v119, v61
	v_add_u32_e32 v61, s19, v59
	v_and_b32_e32 v63, 62, v61
	v_lshl_add_u32 v63, v63, 2, 0
	v_add_u32_e32 v61, s19, v61
	ds_read_b32 v120, v63
	v_and_b32_e32 v63, 61, v61
	v_lshl_add_u32 v63, v63, 2, 0
	v_add_u32_e32 v61, s19, v61
	ds_read_b32 v121, v63
	v_and_b32_e32 v63, 60, v61
	v_lshl_add_u32 v63, v63, 2, 0
	v_add_u32_e32 v61, s19, v61
	ds_read_b32 v106, v63
	v_and_b32_e32 v63, 59, v61
	v_lshl_add_u32 v63, v63, 2, 0
	v_add_u32_e32 v61, s19, v61
	ds_read_b32 v107, v63
	v_and_b32_e32 v63, 58, v61
	v_add_u32_e32 v61, s19, v61
	v_and_b32_e32 v61, 57, v61
	v_lshl_add_u32 v63, v63, 2, 0
	v_lshl_add_u32 v61, v61, 2, 0
	v_add_u32_e32 v59, v59, v77
	ds_read_b32 v102, v63
	ds_read_b32 v103, v61
	v_and_b32_e32 v61, 56, v59
	v_lshl_add_u32 v61, v61, 2, 0
	ds_read_b32 v123, v61
	v_add_u32_e32 v61, s18, v59
	v_and_b32_e32 v63, 48, v61
	v_lshl_add_u32 v63, v63, 2, 0
	v_add_u32_e32 v61, s18, v61
	ds_read_b32 v124, v63
	v_and_b32_e32 v63, 56, v61
	v_lshl_add_u32 v63, v63, 2, 0
	v_lshl_add_u32 v61, s18, 1, v61
	ds_read_b32 v125, v63
	v_and_b32_e32 v63, 56, v61
	v_lshl_add_u32 v63, v63, 2, 0
	v_add_u32_e32 v61, s18, v61
	ds_read_b32 v127, v63
	v_and_b32_e32 v63, 48, v61
	v_add_u32_e32 v61, s18, v61
	v_and_b32_e32 v61, 56, v61
	v_lshl_add_u32 v63, v63, 2, 0
	v_lshl_add_u32 v61, v61, 2, 0
	v_add_u32_e32 v59, v59, v77
	ds_read_b32 v128, v63
	ds_read_b32 v129, v61
	v_and_b32_e32 v61, 57, v59
	v_lshl_add_u32 v61, v61, 2, 0
	ds_read_b32 v85, v61
; __device__ void phase_prep(const Params& p, LAS unsigned char* lds) {
;     ...
;                 for (int dd = 0; dd < 16; ++dd) { const int m = m0 + dd; const float w = wv[dd];
; #pragma unroll
;                     for (int q = 0; q < 8; ++q) a[q] += scr[(m * (8 * co + q)) & 63] * w; }
;             }
	v_add_u32_e32 v61, s15, v59
	v_and_b32_e32 v63, 58, v61
	v_lshl_add_u32 v63, v63, 2, 0
	v_add_u32_e32 v61, s15, v61
	ds_read_b32 v130, v63
	v_and_b32_e32 v63, 59, v61
	v_lshl_add_u32 v63, v63, 2, 0
	v_add_u32_e32 v61, s15, v61
	ds_read_b32 v131, v63
	v_and_b32_e32 v63, 60, v61
	v_lshl_add_u32 v63, v63, 2, 0
	v_add_u32_e32 v61, s15, v61
	ds_read_b32 v132, v63
	v_and_b32_e32 v63, 61, v61
	v_lshl_add_u32 v63, v63, 2, 0
	v_add_u32_e32 v61, s15, v61
	ds_read_b32 v133, v63
	v_and_b32_e32 v63, 62, v61
	v_add_u32_e32 v61, s15, v61
	v_and_b32_e32 v61, 63, v61
	v_lshl_add_u32 v63, v63, 2, 0
	v_lshl_add_u32 v61, v61, 2, 0
	v_add_u32_e32 v59, v59, v77
	ds_read_b32 v134, v63
	ds_read_b32 v135, v61
	v_and_b32_e32 v61, 58, v59
	v_lshl_add_u32 v61, v61, 2, 0
	ds_read_b32 v91, v61
	v_add_u32_e32 v61, s13, v59
	v_and_b32_e32 v63, 52, v61
	v_lshl_add_u32 v63, v63, 2, 0
	v_add_u32_e32 v61, s13, v61
	ds_read_b32 v136, v63
	v_and_b32_e32 v63, 62, v61
	v_lshl_add_u32 v63, v63, 2, 0
	v_add_u32_e32 v61, s13, v61
	ds_read_b32 v137, v63
	v_and_b32_e32 v63, 56, v61
	v_lshl_add_u32 v63, v63, 2, 0
	v_add_u32_e32 v61, s13, v61
	ds_read_b32 v138, v63
	v_and_b32_e32 v63, 50, v61
	v_lshl_add_u32 v63, v63, 2, 0
	v_add_u32_e32 v61, s13, v61
	ds_read_b32 v139, v63
	v_and_b32_e32 v63, 60, v61
	v_add_u32_e32 v61, s13, v61
	v_and_b32_e32 v61, 54, v61
	v_lshl_add_u32 v63, v63, 2, 0
	v_lshl_add_u32 v61, v61, 2, 0
	v_add_u32_e32 v59, v59, v77
	ds_read_b32 v140, v63
	ds_read_b32 v141, v61
	ds_read_b32 v142, v111
	v_and_b32_e32 v61, 59, v59
	v_lshl_add_u32 v61, v61, 2, 0
	ds_read_b32 v143, v61
	v_add_u32_e32 v61, s12, v59
	v_and_b32_e32 v63, 62, v61
	v_lshl_add_u32 v63, v63, 2, 0
	v_add_u32_e32 v61, s12, v61
	ds_read_b32 v144, v63
	v_and_b32_e32 v63, 57, v61
	v_lshl_add_u32 v63, v63, 2, 0
	v_add_u32_e32 v61, s12, v61
	ds_read_b32 v145, v63
	v_and_b32_e32 v63, 60, v61
	v_lshl_add_u32 v63, v63, 2, 0
	v_add_u32_e32 v61, s12, v61
	ds_read_b32 v146, v63
	v_and_b32_e32 v63, 63, v61
	v_lshl_add_u32 v63, v63, 2, 0
	v_add_u32_e32 v61, s12, v61
	ds_read_b32 v147, v63
	v_and_b32_e32 v63, 58, v61
	v_add_u32_e32 v61, s12, v61
	v_and_b32_e32 v61, 61, v61
	v_lshl_add_u32 v63, v63, 2, 0
	v_lshl_add_u32 v61, v61, 2, 0
	v_add_u32_e32 v59, v59, v77
	ds_read_b32 v148, v63
	ds_read_b32 v149, v61
	v_and_b32_e32 v61, 60, v59
	v_lshl_add_u32 v61, v61, 2, 0
	ds_read_b32 v95, v61
	v_add_u32_e32 v61, s11, v59
	v_and_b32_e32 v63, 56, v61
	v_lshl_add_u32 v63, v63, 2, 0
	v_add_u32_e32 v61, s11, v61
	ds_read_b32 v150, v63
	v_and_b32_e32 v63, 52, v61
	v_lshl_add_u32 v63, v63, 2, 0
	v_add_u32_e32 v61, s11, v61
	ds_read_b32 v151, v63
	v_and_b32_e32 v63, 48, v61
	v_lshl_add_u32 v63, v63, 2, 0
	v_add_u32_e32 v61, s11, v61
	ds_read_b32 v152, v63
	v_and_b32_e32 v63, 60, v61
	v_lshl_add_u32 v63, v63, 2, 0
	v_add_u32_e32 v61, s11, v61
	ds_read_b32 v153, v63
	v_and_b32_e32 v63, 40, v61
	v_add_u32_e32 v61, s11, v61
	v_and_b32_e32 v61, 52, v61
	v_lshl_add_u32 v63, v63, 2, 0
	v_lshl_add_u32 v61, v61, 2, 0
	v_add_u32_e32 v59, v59, v77
	ds_read_b32 v154, v63
	ds_read_b32 v155, v61
	ds_read_b32 v156, v112
	v_and_b32_e32 v61, 61, v59
	v_lshl_add_u32 v61, v61, 2, 0
	ds_read_b32 v157, v61
	v_add_u32_e32 v61, s10, v59
	v_and_b32_e32 v63, 58, v61
	v_lshl_add_u32 v63, v63, 2, 0
	v_add_u32_e32 v61, s10, v61
	ds_read_b32 v158, v63
	v_and_b32_e32 v63, 63, v61
	v_lshl_add_u32 v63, v63, 2, 0
	v_add_u32_e32 v61, s10, v61
	ds_read_b32 v159, v63
	v_and_b32_e32 v63, 60, v61
	v_lshl_add_u32 v63, v63, 2, 0
	v_add_u32_e32 v61, s10, v61
	ds_read_b32 v160, v63
	v_and_b32_e32 v63, 57, v61
	v_lshl_add_u32 v63, v63, 2, 0
	v_add_u32_e32 v61, s10, v61
	ds_read_b32 v161, v63
	v_and_b32_e32 v63, 62, v61
	v_add_u32_e32 v61, s10, v61
	v_and_b32_e32 v61, 59, v61
	v_lshl_add_u32 v63, v63, 2, 0
	v_lshl_add_u32 v61, v61, 2, 0
	v_add_u32_e32 v59, v59, v77
	ds_read_b32 v162, v63
	ds_read_b32 v163, v61
	ds_read_b32 v164, v113
	v_and_b32_e32 v61, 62, v59
	v_lshl_add_u32 v61, v61, 2, 0
	ds_read_b32 v165, v61
	v_add_u32_e32 v61, s7, v59
	v_and_b32_e32 v63, 60, v61
	v_lshl_add_u32 v63, v63, 2, 0
	v_add_u32_e32 v61, s7, v61
	ds_read_b32 v166, v63
	v_and_b32_e32 v63, 58, v61
	v_lshl_add_u32 v63, v63, 2, 0
	v_add_u32_e32 v61, s7, v61
	ds_read_b32 v167, v63
	v_and_b32_e32 v63, 56, v61
	v_lshl_add_u32 v63, v63, 2, 0
	v_add_u32_e32 v61, s7, v61
	ds_read_b32 v168, v63
	v_and_b32_e32 v63, 54, v61
	v_lshl_add_u32 v63, v63, 2, 0
	v_add_u32_e32 v61, s7, v61
	ds_read_b32 v169, v63
	v_and_b32_e32 v63, 52, v61
	v_add_u32_e32 v61, s7, v61
	v_and_b32_e32 v61, 50, v61
	v_lshl_add_u32 v63, v63, 2, 0
	v_lshl_add_u32 v61, v61, 2, 0
	v_add_u32_e32 v59, v59, v77
	ds_read_b32 v170, v63
	ds_read_b32 v171, v61
	ds_read_b32 v172, v75
	v_and_b32_e32 v61, 63, v59
	s_waitcnt vmcnt(10) lgkmcnt(14)
	v_pk_fma_f32 v[4:5], v[56:57], v[92:93], v[4:5] op_sel_hi:[0,1,1]
	v_lshl_add_u32 v61, v61, 2, 0
	s_waitcnt vmcnt(9)
; __device__ __forceinline__ unsigned pk2(float lo, float hi) { unsigned r; asm volatile("v_cvt_pk_bf16_f32 %0, %1, %2" : "=v"(r) : "v"(lo), "v"(hi)); return r; }
; __device__ void phase_prep(const Params& p, LAS unsigned char* lds) {
;     ...
;                 for (int dd = 0; dd < 16; ++dd) { const int m = m0 + dd; const float w = wv[dd];
; #pragma unroll
;                     for (int q = 0; q < 8; ++q) a[q] += scr[(m * (8 * co + q)) & 63] * w; }
;             }
;             bf16_t* dst = (bf16_t*)(p.ws + OFF_W + (size_t)l * LW + LW_WM) + (size_t)n * 1280 + 768 + g * 128 + part * 64 + 8 * co;
;             u32x4 o; o.x = pk2(a[0], a[1]); o.y = pk2(a[2], a[3]); o.z = pk2(a[4], a[5]); o.w = pk2(a[6], a[7]);
;             *(u32x4*)dst = o;
	v_pk_fma_f32 v[4:5], v[58:59], v[104:105], v[4:5] op_sel_hi:[0,1,1]
	v_add_u32_e32 v59, s6, v59
	ds_read_b32 v173, v61
	s_waitcnt vmcnt(8)
	v_pk_fma_f32 v[4:5], v[60:61], v[118:119], v[4:5] op_sel_hi:[0,1,1]
	v_mov_b32_e32 v122, v78
	v_and_b32_e32 v61, 62, v59
	s_waitcnt vmcnt(7)
	v_pk_fma_f32 v[4:5], v[62:63], v[122:123], v[4:5] op_sel_hi:[0,1,1]
	v_lshl_add_u32 v61, v61, 2, 0
	v_add_u32_e32 v59, s6, v59
	s_waitcnt vmcnt(6)
	v_pk_fma_f32 v[4:5], v[64:65], v[84:85], v[4:5] op_sel_hi:[0,1,1]
	ds_read_b32 v84, v61
	v_and_b32_e32 v61, 61, v59
	v_pk_fma_f32 v[50:51], v[56:57], v[86:87], v[50:51] op_sel_hi:[0,1,1]
	v_lshl_add_u32 v61, v61, 2, 0
	v_pk_fma_f32 v[50:51], v[58:59], v[100:101], v[50:51] op_sel_hi:[0,1,1]
	v_pk_fma_f32 v[50:51], v[60:61], v[120:121], v[50:51] op_sel_hi:[0,1,1]
	v_pk_fma_f32 v[50:51], v[62:63], v[124:125], v[50:51] op_sel_hi:[0,1,1]
	v_pk_fma_f32 v[50:51], v[64:65], v[130:131], v[50:51] op_sel_hi:[0,1,1]
	ds_read_b32 v85, v61
	s_waitcnt vmcnt(5)
	v_pk_fma_f32 v[50:51], v[66:67], v[136:137], v[50:51] op_sel_hi:[0,1,1]
	s_waitcnt vmcnt(4)
	v_pk_fma_f32 v[50:51], v[68:69], v[144:145], v[50:51] op_sel_hi:[0,1,1]
	s_waitcnt vmcnt(3)
	v_pk_fma_f32 v[50:51], v[70:71], v[150:151], v[50:51] op_sel_hi:[0,1,1]
	v_add_u32_e32 v59, s6, v59
	s_waitcnt vmcnt(2) lgkmcnt(14)
	v_pk_fma_f32 v[50:51], v[72:73], v[158:159], v[50:51] op_sel_hi:[0,1,1]
	v_and_b32_e32 v61, 60, v59
	s_waitcnt vmcnt(1) lgkmcnt(8)
	v_pk_fma_f32 v[50:51], v[74:75], v[166:167], v[50:51] op_sel_hi:[0,1,1]
	v_lshl_add_u32 v61, v61, 2, 0
	v_add_u32_e32 v59, s6, v59
	s_waitcnt vmcnt(0) lgkmcnt(0)
	v_pk_fma_f32 v[50:51], v[76:77], v[84:85], v[50:51] op_sel_hi:[0,1,1]
	ds_read_b32 v84, v61
	v_and_b32_e32 v61, 59, v59
	v_pk_fma_f32 v[54:55], v[56:57], v[82:83], v[54:55] op_sel_hi:[0,1,1]
	v_lshl_add_u32 v61, v61, 2, 0
	v_pk_fma_f32 v[54:55], v[58:59], v[98:99], v[54:55] op_sel_hi:[0,1,1]
	v_add_u32_e32 v59, s6, v59
	ds_read_b32 v85, v61
	v_pk_fma_f32 v[54:55], v[60:61], v[106:107], v[54:55] op_sel_hi:[0,1,1]
	v_and_b32_e32 v61, 58, v59
	v_add_u32_e32 v59, s6, v59
	v_and_b32_e32 v59, 57, v59
	v_lshl_add_u32 v59, v59, 2, 0
	v_pk_fma_f32 v[52:53], v[56:57], v[80:81], v[52:53] op_sel_hi:[0,1,1]
	v_lshl_add_u32 v61, v61, 2, 0
	v_pk_fma_f32 v[52:53], v[58:59], v[88:89], v[52:53] op_sel_hi:[0,1,1]
	v_mov_b32_e32 v126, v79
	v_pk_fma_f32 v[52:53], v[60:61], v[102:103], v[52:53] op_sel_hi:[0,1,1]
	v_pk_fma_f32 v[54:55], v[62:63], v[126:127], v[54:55] op_sel_hi:[0,1,1]
	v_pk_fma_f32 v[52:53], v[62:63], v[128:129], v[52:53] op_sel_hi:[0,1,1]
	v_pk_fma_f32 v[54:55], v[64:65], v[132:133], v[54:55] op_sel_hi:[0,1,1]
	v_pk_fma_f32 v[52:53], v[64:65], v[134:135], v[52:53] op_sel_hi:[0,1,1]
	v_pk_fma_f32 v[4:5], v[66:67], v[90:91], v[4:5] op_sel_hi:[0,1,1]
	v_pk_fma_f32 v[54:55], v[66:67], v[138:139], v[54:55] op_sel_hi:[0,1,1]
	ds_read_b32 v78, v61
	ds_read_b32 v79, v59
	v_pk_fma_f32 v[52:53], v[66:67], v[140:141], v[52:53] op_sel_hi:[0,1,1]
	v_pk_fma_f32 v[4:5], v[68:69], v[142:143], v[4:5] op_sel_hi:[0,1,1]
	v_pk_fma_f32 v[54:55], v[68:69], v[146:147], v[54:55] op_sel_hi:[0,1,1]
	v_pk_fma_f32 v[52:53], v[68:69], v[148:149], v[52:53] op_sel_hi:[0,1,1]
	v_pk_fma_f32 v[4:5], v[70:71], v[94:95], v[4:5] op_sel_hi:[0,1,1]
	v_pk_fma_f32 v[54:55], v[70:71], v[152:153], v[54:55] op_sel_hi:[0,1,1]
	v_pk_fma_f32 v[52:53], v[70:71], v[154:155], v[52:53] op_sel_hi:[0,1,1]
	v_pk_fma_f32 v[4:5], v[72:73], v[156:157], v[4:5] op_sel_hi:[0,1,1]
	v_pk_fma_f32 v[54:55], v[72:73], v[160:161], v[54:55] op_sel_hi:[0,1,1]
	v_pk_fma_f32 v[52:53], v[72:73], v[162:163], v[52:53] op_sel_hi:[0,1,1]
	v_pk_fma_f32 v[4:5], v[74:75], v[164:165], v[4:5] op_sel_hi:[0,1,1]
	v_pk_fma_f32 v[54:55], v[74:75], v[168:169], v[54:55] op_sel_hi:[0,1,1]
	v_pk_fma_f32 v[52:53], v[74:75], v[170:171], v[52:53] op_sel_hi:[0,1,1]
	s_add_i32 s2, s1, 16
	v_pk_fma_f32 v[4:5], v[76:77], v[172:173], v[4:5] op_sel_hi:[0,1,1]
	s_waitcnt lgkmcnt(2)
	v_pk_fma_f32 v[54:55], v[76:77], v[84:85], v[54:55] op_sel_hi:[0,1,1]
	s_waitcnt lgkmcnt(0)
	v_pk_fma_f32 v[52:53], v[76:77], v[78:79], v[52:53] op_sel_hi:[0,1,1]
	s_cmp_gt_u32 s1, 47
	s_mov_b32 s1, s2
	s_cbranch_scc0 .LBB0_693
	s_mul_hi_u32 s1, s0, 0x1d80000
	s_mul_i32 s0, s0, 0x1d80000
	v_lshl_add_u64 v[2:3], v[24:25], 0, s[0:1]
	v_mad_u64_u32 v[2:3], s[0:1], v57, s38, v[2:3]
	s_lshl_b32 s2, s5, 8
	v_lshl_add_u64 v[2:3], v[2:3], 0, s[2:3]
	s_lshl_b32 s2, s4, 3
	v_lshl_add_u64 v[2:3], v[2:3], 0, s[2:3]
	v_lshl_add_u64 v[56:57], v[32:33], 2, v[2:3]
	v_cvt_pk_bf16_f32 v2, v4, v5
	v_cvt_pk_bf16_f32 v3, v50, v51
	v_add_co_u32_e32 v50, vcc, 0xe80000, v56
	v_cvt_pk_bf16_f32 v4, v54, v55
	v_cvt_pk_bf16_f32 v5, v52, v53
	s_nop 1
	v_addc_co_u32_e32 v51, vcc, 0, v57, vcc
	global_store_dwordx2 v[50:51], v[2:3], off offset:1536
	global_store_dwordx2 v[50:51], v[4:5], off offset:1552
	s_waitcnt lgkmcnt(0)
	s_barrier
